# G1 rotary epilogue: the two cos/sin rounds of a token group requested together (counted vmcnt), 4 instead of 8 exposed round trips per q/k tile
# baseline (speedup 1.0000x reference)
.LBB0_251:
	v_lshl_add_u32 v16, s12, 7, v7
	v_ashrrev_i32_e32 v17, 31, v16
	v_lshlrev_b64 v[140:141], 7, v[16:17]
	v_lshl_add_u64 v[160:161], v[0:1], 0, v[140:141]
	v_lshl_add_u64 v[162:163], v[4:5], 0, v[140:141]
	global_load_dwordx4 v[152:155], v[160:161], off
	global_load_dwordx4 v[156:159], v[162:163], off
	global_load_dwordx4 v[166:169], v[160:161], off offset:64
	global_load_dwordx4 v[170:173], v[162:163], off offset:64
	s_waitcnt vmcnt(2)
	v_pk_mul_f32 v[140:141], v[90:91], v[158:159]
	v_pk_mul_f32 v[164:165], v[88:89], v[156:157]
	v_pk_fma_f32 v[142:143], v[150:151], v[154:155], v[140:141] neg_lo:[0,0,1] neg_hi:[0,0,1]
	v_pk_fma_f32 v[140:141], v[148:149], v[152:153], v[164:165] neg_lo:[0,0,1] neg_hi:[0,0,1]
	v_pk_mul_f32 v[150:151], v[150:151], v[158:159]
	v_pk_mul_f32 v[148:149], v[148:149], v[156:157]
	v_pk_fma_f32 v[90:91], v[90:91], v[154:155], v[150:151]
	v_pk_fma_f32 v[88:89], v[88:89], v[152:153], v[148:149]
	s_waitcnt vmcnt(0)
	v_pk_mul_f32 v[148:149], v[86:87], v[172:173]
	v_pk_mul_f32 v[160:161], v[84:85], v[170:171]
	v_pk_fma_f32 v[150:151], v[146:147], v[168:169], v[148:149] neg_lo:[0,0,1] neg_hi:[0,0,1]
	v_pk_fma_f32 v[148:149], v[144:145], v[166:167], v[160:161] neg_lo:[0,0,1] neg_hi:[0,0,1]
	v_pk_mul_f32 v[144:145], v[144:145], v[170:171]
	v_pk_mul_f32 v[146:147], v[146:147], v[172:173]
	v_pk_fma_f32 v[84:85], v[84:85], v[166:167], v[144:145]
	v_or_b32_e32 v144, 16, v16
	v_ashrrev_i32_e32 v145, 31, v144
	v_lshlrev_b64 v[144:145], 7, v[144:145]
	v_lshl_add_u64 v[160:161], v[0:1], 0, v[144:145]
	v_pk_fma_f32 v[86:87], v[86:87], v[168:169], v[146:147]
	v_lshl_add_u64 v[162:163], v[4:5], 0, v[144:145]
	global_load_dwordx4 v[152:155], v[160:161], off
	global_load_dwordx4 v[156:159], v[162:163], off
	global_load_dwordx4 v[166:169], v[160:161], off offset:64
	global_load_dwordx4 v[170:173], v[162:163], off offset:64
	s_waitcnt vmcnt(2)
	v_pk_mul_f32 v[144:145], v[98:99], v[158:159]
	v_pk_mul_f32 v[164:165], v[96:97], v[156:157]
	v_pk_fma_f32 v[146:147], v[138:139], v[154:155], v[144:145] neg_lo:[0,0,1] neg_hi:[0,0,1]
	v_pk_fma_f32 v[144:145], v[136:137], v[152:153], v[164:165] neg_lo:[0,0,1] neg_hi:[0,0,1]
	v_pk_mul_f32 v[138:139], v[138:139], v[158:159]
	v_pk_mul_f32 v[136:137], v[136:137], v[156:157]
	v_pk_fma_f32 v[98:99], v[98:99], v[154:155], v[138:139]
	v_pk_fma_f32 v[96:97], v[96:97], v[152:153], v[136:137]
	s_waitcnt vmcnt(0)
	v_pk_mul_f32 v[136:137], v[94:95], v[172:173]
	v_pk_mul_f32 v[160:161], v[92:93], v[170:171]
	v_pk_fma_f32 v[138:139], v[134:135], v[168:169], v[136:137] neg_lo:[0,0,1] neg_hi:[0,0,1]
	v_pk_fma_f32 v[136:137], v[132:133], v[166:167], v[160:161] neg_lo:[0,0,1] neg_hi:[0,0,1]
	v_pk_mul_f32 v[132:133], v[132:133], v[170:171]
	v_pk_mul_f32 v[134:135], v[134:135], v[172:173]
	v_pk_fma_f32 v[92:93], v[92:93], v[166:167], v[132:133]
	v_or_b32_e32 v132, 32, v16
	v_ashrrev_i32_e32 v133, 31, v132
	v_lshlrev_b64 v[132:133], 7, v[132:133]
	v_lshl_add_u64 v[160:161], v[0:1], 0, v[132:133]
	v_pk_fma_f32 v[94:95], v[94:95], v[168:169], v[134:135]
	v_lshl_add_u64 v[162:163], v[4:5], 0, v[132:133]
	global_load_dwordx4 v[152:155], v[160:161], off
	global_load_dwordx4 v[156:159], v[162:163], off
	global_load_dwordx4 v[166:169], v[160:161], off offset:64
	global_load_dwordx4 v[170:173], v[162:163], off offset:64
	v_or_b32_e32 v16, 48, v16
	v_ashrrev_i32_e32 v17, 31, v16
	v_lshlrev_b64 v[16:17], 7, v[16:17]
	s_waitcnt vmcnt(2)
	v_pk_mul_f32 v[132:133], v[106:107], v[158:159]
	v_pk_mul_f32 v[164:165], v[104:105], v[156:157]
	v_pk_fma_f32 v[134:135], v[130:131], v[154:155], v[132:133] neg_lo:[0,0,1] neg_hi:[0,0,1]
	v_pk_fma_f32 v[132:133], v[128:129], v[152:153], v[164:165] neg_lo:[0,0,1] neg_hi:[0,0,1]
	v_pk_mul_f32 v[130:131], v[130:131], v[158:159]
	v_pk_mul_f32 v[128:129], v[128:129], v[156:157]
	v_pk_fma_f32 v[106:107], v[106:107], v[154:155], v[130:131]
	v_pk_fma_f32 v[104:105], v[104:105], v[152:153], v[128:129]
	s_waitcnt vmcnt(0)
	v_pk_mul_f32 v[128:129], v[102:103], v[172:173]
	v_pk_mul_f32 v[160:161], v[100:101], v[170:171]
	v_pk_fma_f32 v[130:131], v[126:127], v[168:169], v[128:129] neg_lo:[0,0,1] neg_hi:[0,0,1]
	v_pk_fma_f32 v[128:129], v[124:125], v[166:167], v[160:161] neg_lo:[0,0,1] neg_hi:[0,0,1]
	v_pk_mul_f32 v[126:127], v[126:127], v[172:173]
	v_pk_mul_f32 v[124:125], v[124:125], v[170:171]
	v_lshl_add_u64 v[160:161], v[0:1], 0, v[16:17]
	v_pk_fma_f32 v[102:103], v[102:103], v[168:169], v[126:127]
	v_pk_fma_f32 v[100:101], v[100:101], v[166:167], v[124:125]
	v_lshl_add_u64 v[16:17], v[4:5], 0, v[16:17]
	global_load_dwordx4 v[152:155], v[160:161], off
	global_load_dwordx4 v[156:159], v[16:17], off
	global_load_dwordx4 v[166:169], v[160:161], off offset:64
	global_load_dwordx4 v[170:173], v[16:17], off offset:64
	s_waitcnt vmcnt(2)
	v_pk_mul_f32 v[124:125], v[114:115], v[158:159]
	v_pk_mul_f32 v[162:163], v[112:113], v[156:157]
	v_pk_fma_f32 v[126:127], v[122:123], v[154:155], v[124:125] neg_lo:[0,0,1] neg_hi:[0,0,1]
	v_pk_fma_f32 v[124:125], v[120:121], v[152:153], v[162:163] neg_lo:[0,0,1] neg_hi:[0,0,1]
	v_pk_mul_f32 v[122:123], v[122:123], v[158:159]
	v_pk_mul_f32 v[120:121], v[120:121], v[156:157]
	v_pk_fma_f32 v[114:115], v[114:115], v[154:155], v[122:123]
	v_pk_fma_f32 v[112:113], v[112:113], v[152:153], v[120:121]
	s_waitcnt vmcnt(0)
	v_pk_mul_f32 v[16:17], v[110:111], v[172:173]
	v_pk_mul_f32 v[156:157], v[108:109], v[170:171]
	v_pk_fma_f32 v[158:159], v[118:119], v[168:169], v[16:17] neg_lo:[0,0,1] neg_hi:[0,0,1]
	v_pk_fma_f32 v[156:157], v[116:117], v[166:167], v[156:157] neg_lo:[0,0,1] neg_hi:[0,0,1]
	v_pk_mul_f32 v[16:17], v[118:119], v[172:173]
	v_pk_mul_f32 v[116:117], v[116:117], v[170:171]
	v_pk_fma_f32 v[110:111], v[110:111], v[168:169], v[16:17]
	v_pk_fma_f32 v[108:109], v[108:109], v[166:167], v[116:117]
	v_mov_b64_e32 v[120:121], v[124:125]
	v_mov_b64_e32 v[122:123], v[126:127]
	v_mov_b64_e32 v[124:125], v[128:129]
	v_mov_b64_e32 v[126:127], v[130:131]
	v_mov_b64_e32 v[128:129], v[132:133]
	v_mov_b64_e32 v[130:131], v[134:135]
	v_mov_b64_e32 v[132:133], v[136:137]
	v_mov_b64_e32 v[134:135], v[138:139]
	v_mov_b64_e32 v[136:137], v[144:145]
	v_mov_b64_e32 v[138:139], v[146:147]
	v_mov_b64_e32 v[144:145], v[148:149]
	v_mov_b64_e32 v[116:117], v[156:157]
	v_mov_b64_e32 v[146:147], v[150:151]
	v_mov_b64_e32 v[150:151], v[142:143]
	v_mov_b64_e32 v[118:119], v[158:159]
	v_mov_b64_e32 v[148:149], v[140:141]
	s_and_b32 s2, s44, -2
	s_cmp_eq_u32 s2, 2
	s_mov_b64 s[2:3], -1
	s_cbranch_scc1 .LBB0_247
